# W_UQ / W_UKV conversion loops: the eight per-row scale loads issued together (were eight serialized round trips on the straggler waves); prep rope loads merged
# baseline (speedup 1.0000x reference)
.LBB0_45:
	s_mul_hi_i32 s6, s19, 0x2aaaaaab
	s_lshr_b32 s7, s6, 31
	s_ashr_i32 s6, s6, 1
	s_add_i32 s6, s6, s7
	s_lshl_b32 s8, s6, 6
	s_mulk_i32 s6, 0xfe80
	s_add_i32 s6, s17, s6
	s_ashr_i32 s7, s6, 31
	v_or_b32_e32 v34, s8, v38
	v_lshl_add_u64 v[2:3], s[6:7], 2, v[44:45]
	v_mad_i64_i32 v[4:5], s[10:11], v34, s18, v[2:3]
	v_or_b32_e32 v6, 8, v34
	v_mad_i64_i32 v[6:7], s[10:11], v6, s18, v[2:3]
	global_load_dwordx4 v[26:29], v[4:5], off nt
	global_load_dwordx4 v[30:33], v[6:7], off nt
	v_or_b32_e32 v4, 16, v34
	v_mad_i64_i32 v[4:5], s[10:11], v4, s18, v[2:3]
	v_or_b32_e32 v6, 24, v34
	v_mad_i64_i32 v[6:7], s[10:11], v6, s18, v[2:3]
	global_load_dwordx4 v[18:21], v[4:5], off nt
	global_load_dwordx4 v[22:25], v[6:7], off nt
	v_or_b32_e32 v4, 32, v34
	v_mad_i64_i32 v[4:5], s[10:11], v4, s18, v[2:3]
	v_or_b32_e32 v6, 40, v34
	v_mad_i64_i32 v[6:7], s[10:11], v6, s18, v[2:3]
	global_load_dwordx4 v[10:13], v[4:5], off nt
	global_load_dwordx4 v[14:17], v[6:7], off nt
	v_or_b32_e32 v4, 48, v34
	v_mad_i64_i32 v[36:37], s[10:11], v4, s18, v[2:3]
	v_or_b32_e32 v4, 56, v34
	v_mad_i64_i32 v[70:71], s[10:11], v4, s18, v[2:3]
	global_load_dwordx4 v[6:9], v[36:37], off nt
	global_load_dwordx4 v[2:5], v[70:71], off nt
	s_and_b64 vcc, exec, s[0:1]
	s_cbranch_vccnz .LBB0_56
	v_ashrrev_i32_e32 v35, 31, v34
	v_lshl_add_u64 v[34:35], v[34:35], 2, s[4:5]
	v_mov_b64_e32 v[196:197], v[34:35]
	global_load_dword v176, v[196:197], off
	global_load_dword v178, v[196:197], off offset:32
	global_load_dword v180, v[196:197], off offset:64
	global_load_dword v182, v[196:197], off offset:96
	global_load_dword v184, v[196:197], off offset:128
	global_load_dword v186, v[196:197], off offset:160
	global_load_dword v192, v[196:197], off offset:192
	global_load_dword v194, v[196:197], off offset:224
	s_waitcnt vmcnt(0) lgkmcnt(0)
	v_or_b32_e32 v36, s8, v49
	v_ashrrev_i32_e32 v37, 31, v36
	v_lshl_add_u64 v[36:37], v[36:37], 2, s[4:5]
	v_pk_mul_f32 v[70:71], v[28:29], v[176:177] op_sel_hi:[1,0]
	v_pk_mul_f32 v[34:35], v[26:27], v[176:177] op_sel_hi:[1,0]
	ds_write2_b32 v56, v34, v35 offset1:1
	ds_write2_b32 v56, v70, v71 offset0:2 offset1:3
	v_pk_mul_f32 v[36:37], v[32:33], v[178:179] op_sel_hi:[1,0]
	v_pk_mul_f32 v[34:35], v[30:31], v[178:179] op_sel_hi:[1,0]
	s_cbranch_execnz .LBB0_48

.LBB0_48:
	s_and_b64 vcc, exec, s[0:1]
	ds_write2_b32 v57, v34, v35 offset1:1
	ds_write2_b32 v57, v36, v37 offset0:2 offset1:3
	s_cbranch_vccnz .LBB0_57
	s_waitcnt vmcnt(0) lgkmcnt(0)
	v_or_b32_e32 v26, s8, v50
	v_ashrrev_i32_e32 v27, 31, v26
	v_lshl_add_u64 v[26:27], v[26:27], 2, s[4:5]
	v_or_b32_e32 v28, s8, v51
	v_ashrrev_i32_e32 v29, 31, v28
	v_lshl_add_u64 v[28:29], v[28:29], 2, s[4:5]
	v_pk_mul_f32 v[30:31], v[20:21], v[180:181] op_sel_hi:[1,0]
	v_pk_mul_f32 v[26:27], v[18:19], v[180:181] op_sel_hi:[1,0]
	ds_write2_b32 v58, v26, v27 offset1:1
	ds_write2_b32 v58, v30, v31 offset0:2 offset1:3
	v_pk_mul_f32 v[28:29], v[24:25], v[182:183] op_sel_hi:[1,0]
	v_pk_mul_f32 v[26:27], v[22:23], v[182:183] op_sel_hi:[1,0]
	s_cbranch_execnz .LBB0_51

.LBB0_51:
	s_and_b64 vcc, exec, s[0:1]
	s_waitcnt vmcnt(0) lgkmcnt(0)
	ds_write2_b32 v59, v26, v27 offset1:1
	ds_write2_b32 v59, v28, v29 offset0:2 offset1:3
	s_cbranch_vccnz .LBB0_58
	s_ashr_i32 s9, s8, 31
	v_lshl_add_u64 v[18:19], s[8:9], 0, v[38:39]
	v_lshl_add_u64 v[18:19], v[18:19], 2, s[4:5]
	v_pk_mul_f32 v[22:23], v[12:13], v[184:185] op_sel_hi:[1,0]
	v_pk_mul_f32 v[20:21], v[10:11], v[184:185] op_sel_hi:[1,0]
	ds_write2_b32 v67, v20, v21 offset1:1
	ds_write2_b32 v67, v22, v23 offset0:2 offset1:3
	v_pk_mul_f32 v[20:21], v[16:17], v[186:187] op_sel_hi:[1,0]
	v_pk_mul_f32 v[18:19], v[14:15], v[186:187] op_sel_hi:[1,0]
	s_cbranch_execnz .LBB0_54

.LBB0_54:
	s_and_b64 vcc, exec, s[0:1]
	ds_write2_b32 v65, v18, v19 offset1:1
	ds_write2_b32 v65, v20, v21 offset0:2 offset1:3
	s_cbranch_vccnz .LBB0_59
	s_ashr_i32 s9, s8, 31
	v_lshl_add_u64 v[10:11], s[8:9], 0, v[38:39]
	v_lshl_add_u64 v[10:11], v[10:11], 2, s[4:5]
	v_pk_mul_f32 v[14:15], v[8:9], v[192:193] op_sel_hi:[1,0]
	v_pk_mul_f32 v[12:13], v[6:7], v[192:193] op_sel_hi:[1,0]
	ds_write2_b32 v68, v12, v13 offset1:1
	ds_write2_b32 v68, v14, v15 offset0:2 offset1:3
	v_pk_mul_f32 v[12:13], v[4:5], v[194:195] op_sel_hi:[1,0]
	v_pk_mul_f32 v[10:11], v[2:3], v[194:195] op_sel_hi:[1,0]
	s_cbranch_execnz .LBB0_44
	s_branch .LBB0_60

.LBB0_64:
	s_ashr_i32 s8, s18, 31
	s_lshr_b32 s8, s8, 28
	s_add_i32 s8, s18, s8
	s_ashr_i32 s9, s8, 4
	s_lshl_b32 s8, s9, 6
	s_lshl_b32 s19, s9, 9
	s_sub_i32 s10, s17, s19
	v_or_b32_e32 v34, s8, v38
	s_ashr_i32 s11, s10, 31
	v_ashrrev_i32_e32 v35, 31, v34
	v_or_b32_e32 v6, 8, v34
	v_lshl_add_u64 v[2:3], s[10:11], 2, v[40:41]
	v_lshlrev_b64 v[4:5], 11, v[34:35]
	v_ashrrev_i32_e32 v7, 31, v6
	v_lshl_add_u64 v[4:5], v[2:3], 0, v[4:5]
	v_lshlrev_b64 v[6:7], 11, v[6:7]
	v_lshl_add_u64 v[6:7], v[2:3], 0, v[6:7]
	global_load_dwordx4 v[26:29], v[4:5], off nt
	global_load_dwordx4 v[30:33], v[6:7], off nt
	v_or_b32_e32 v4, 16, v34
	v_ashrrev_i32_e32 v5, 31, v4
	v_or_b32_e32 v6, 24, v34
	v_lshlrev_b64 v[4:5], 11, v[4:5]
	v_ashrrev_i32_e32 v7, 31, v6
	v_lshl_add_u64 v[4:5], v[2:3], 0, v[4:5]
	v_lshlrev_b64 v[6:7], 11, v[6:7]
	v_lshl_add_u64 v[6:7], v[2:3], 0, v[6:7]
	global_load_dwordx4 v[18:21], v[4:5], off nt
	global_load_dwordx4 v[22:25], v[6:7], off nt
	v_or_b32_e32 v4, 32, v34
	v_ashrrev_i32_e32 v5, 31, v4
	v_or_b32_e32 v6, 40, v34
	v_lshlrev_b64 v[4:5], 11, v[4:5]
	v_ashrrev_i32_e32 v7, 31, v6
	v_lshl_add_u64 v[4:5], v[2:3], 0, v[4:5]
	v_lshlrev_b64 v[6:7], 11, v[6:7]
	v_lshl_add_u64 v[6:7], v[2:3], 0, v[6:7]
	global_load_dwordx4 v[10:13], v[4:5], off nt
	global_load_dwordx4 v[14:17], v[6:7], off nt
	v_or_b32_e32 v4, 48, v34
	v_ashrrev_i32_e32 v5, 31, v4
	v_lshlrev_b64 v[4:5], 11, v[4:5]
	v_lshl_add_u64 v[36:37], v[2:3], 0, v[4:5]
	v_or_b32_e32 v4, 56, v34
	v_ashrrev_i32_e32 v5, 31, v4
	v_lshlrev_b64 v[4:5], 11, v[4:5]
	v_lshl_add_u64 v[60:61], v[2:3], 0, v[4:5]
	global_load_dwordx4 v[6:9], v[36:37], off nt
	global_load_dwordx4 v[2:5], v[60:61], off nt
	s_and_b64 vcc, exec, s[0:1]
	s_cbranch_vccnz .LBB0_75
	v_lshl_add_u64 v[34:35], v[34:35], 2, s[4:5]
	v_mov_b64_e32 v[196:197], v[34:35]
	global_load_dword v176, v[196:197], off
	global_load_dword v178, v[196:197], off offset:32
	global_load_dword v180, v[196:197], off offset:64
	global_load_dword v182, v[196:197], off offset:96
	global_load_dword v184, v[196:197], off offset:128
	global_load_dword v186, v[196:197], off offset:160
	global_load_dword v192, v[196:197], off offset:192
	global_load_dword v194, v[196:197], off offset:224
	s_waitcnt vmcnt(0) lgkmcnt(0)
	v_or_b32_e32 v36, s8, v49
	v_ashrrev_i32_e32 v37, 31, v36
	v_lshl_add_u64 v[36:37], v[36:37], 2, s[4:5]
	v_pk_mul_f32 v[60:61], v[28:29], v[176:177] op_sel_hi:[1,0]
	v_pk_mul_f32 v[34:35], v[26:27], v[176:177] op_sel_hi:[1,0]
	ds_write2_b32 v56, v34, v35 offset1:1
	ds_write2_b32 v56, v60, v61 offset0:2 offset1:3
	v_pk_mul_f32 v[36:37], v[32:33], v[178:179] op_sel_hi:[1,0]
	v_pk_mul_f32 v[34:35], v[30:31], v[178:179] op_sel_hi:[1,0]
	s_cbranch_execnz .LBB0_67

.LBB0_70:
	s_and_b64 vcc, exec, s[0:1]
	s_waitcnt vmcnt(0) lgkmcnt(0)
	ds_write2_b32 v59, v26, v27 offset1:1
	ds_write2_b32 v59, v28, v29 offset0:2 offset1:3
	s_cbranch_vccnz .LBB0_77
	s_ashr_i32 s9, s8, 31
	v_lshl_add_u64 v[18:19], s[8:9], 0, v[38:39]
	v_lshl_add_u64 v[18:19], v[18:19], 2, s[4:5]
	v_pk_mul_f32 v[22:23], v[12:13], v[184:185] op_sel_hi:[1,0]
	v_pk_mul_f32 v[20:21], v[10:11], v[184:185] op_sel_hi:[1,0]
	ds_write2_b32 v46, v20, v21 offset1:1
	ds_write2_b32 v46, v22, v23 offset0:2 offset1:3
	v_pk_mul_f32 v[20:21], v[16:17], v[186:187] op_sel_hi:[1,0]
	v_pk_mul_f32 v[18:19], v[14:15], v[186:187] op_sel_hi:[1,0]
	s_cbranch_execnz .LBB0_73

.LBB0_73:
	s_and_b64 vcc, exec, s[0:1]
	ds_write2_b32 v44, v18, v19 offset1:1
	ds_write2_b32 v44, v20, v21 offset0:2 offset1:3
	s_cbranch_vccnz .LBB0_78
	s_ashr_i32 s9, s8, 31
	v_lshl_add_u64 v[10:11], s[8:9], 0, v[38:39]
	v_lshl_add_u64 v[10:11], v[10:11], 2, s[4:5]
	v_pk_mul_f32 v[14:15], v[8:9], v[192:193] op_sel_hi:[1,0]
	v_pk_mul_f32 v[12:13], v[6:7], v[192:193] op_sel_hi:[1,0]
	ds_write2_b32 v47, v12, v13 offset1:1
	ds_write2_b32 v47, v14, v15 offset0:2 offset1:3
	v_pk_mul_f32 v[12:13], v[4:5], v[194:195] op_sel_hi:[1,0]
	v_pk_mul_f32 v[10:11], v[2:3], v[194:195] op_sel_hi:[1,0]
	s_cbranch_execnz .LBB0_63
	s_branch .LBB0_79

.LBB0_290:
	s_or_b64 exec, exec, s[14:15]
	s_and_saveexec_b64 s[6:7], s[12:13]
	s_cbranch_execz .LBB0_287
	v_mov_b32_e32 v13, v233
	s_waitcnt lgkmcnt(0)
	v_lshl_add_u64 v[0:1], v[16:17], 0, v[12:13]
	global_load_dwordx2 v[16:17], v[0:1], off offset:768
	global_load_dwordx2 v[26:27], v[0:1], off offset:800
	v_and_b32_e32 v0, 0x1fff0, v20
	v_lshlrev_b32_e32 v22, 2, v0
	v_mov_b32_e32 v23, v233
	v_lshl_add_u64 v[0:1], v[4:5], 0, v[22:23]
	v_lshl_add_u64 v[22:23], v[6:7], 0, v[22:23]
	global_load_dwordx4 v[0:3], v[0:1], off
	global_load_dwordx4 v[22:25], v[22:23], off
	s_waitcnt vmcnt(0) lgkmcnt(0)
	v_lshlrev_b32_e32 v28, 16, v16
	v_lshlrev_b32_e32 v30, 16, v26
	v_and_b32_e32 v31, 0xffff0000, v26
	v_and_b32_e32 v29, 0xffff0000, v16
	v_lshlrev_b32_e32 v26, 16, v27
	v_and_b32_e32 v27, 0xffff0000, v27
	v_pk_mul_f32 v[32:33], v[22:23], v[30:31]
	s_nop 0
	v_pk_fma_f32 v[32:33], v[0:1], v[28:29], v[32:33] neg_lo:[0,0,1] neg_hi:[0,0,1]
	v_pk_mul_f32 v[0:1], v[0:1], v[30:31]
	v_cvt_pk_bf16_f32 v16, v32, v33
	v_pk_fma_f32 v[0:1], v[22:23], v[28:29], v[0:1]
	v_lshlrev_b32_e32 v22, 16, v17
	v_and_b32_e32 v23, 0xffff0000, v17
	v_pk_mul_f32 v[28:29], v[24:25], v[26:27]
	v_cvt_pk_bf16_f32 v0, v0, v1
	v_pk_fma_f32 v[28:29], v[2:3], v[22:23], v[28:29] neg_lo:[0,0,1] neg_hi:[0,0,1]
	v_pk_mul_f32 v[2:3], v[2:3], v[26:27]
	v_cvt_pk_bf16_f32 v17, v28, v29
	v_pk_fma_f32 v[2:3], v[24:25], v[22:23], v[2:3]
	s_nop 0
	v_cvt_pk_bf16_f32 v1, v2, v3
	v_lshlrev_b64 v[2:3], 6, v[14:15]
	v_lshl_add_u64 v[2:3], v[8:9], 0, v[2:3]
	global_store_dwordx2 v[2:3], v[16:17], off
	global_store_dwordx2 v[2:3], v[0:1], off offset:32
	s_branch .LBB0_287

.LBB0_1608:
	s_mul_hi_i32 s2, s19, 0x2aaaaaab
	s_lshr_b32 s3, s2, 31
	s_ashr_i32 s2, s2, 1
	s_add_i32 s2, s2, s3
	s_lshl_b32 s12, s2, 6
	s_mulk_i32 s2, 0xfe80
	s_add_i32 s10, s17, s2
	v_or_b32_e32 v32, s12, v40
	s_ashr_i32 s11, s10, 31
	v_lshl_add_u64 v[0:1], s[10:11], 2, v[42:43]
	v_or_b32_e32 v4, 8, v32
	v_mad_i64_i32 v[2:3], s[2:3], v32, s31, v[0:1]
	v_mad_i64_i32 v[4:5], s[2:3], v4, s31, v[0:1]
	global_load_dwordx4 v[24:27], v[2:3], off nt
	global_load_dwordx4 v[28:31], v[4:5], off nt
	v_or_b32_e32 v2, 16, v32
	v_or_b32_e32 v4, 24, v32
	v_mad_i64_i32 v[2:3], s[2:3], v2, s31, v[0:1]
	v_mad_i64_i32 v[4:5], s[2:3], v4, s31, v[0:1]
	global_load_dwordx4 v[16:19], v[2:3], off nt
	global_load_dwordx4 v[20:23], v[4:5], off nt
	v_or_b32_e32 v2, 32, v32
	v_or_b32_e32 v4, 40, v32
	v_mad_i64_i32 v[2:3], s[2:3], v2, s31, v[0:1]
	v_mad_i64_i32 v[4:5], s[2:3], v4, s31, v[0:1]
	global_load_dwordx4 v[8:11], v[2:3], off nt
	global_load_dwordx4 v[12:15], v[4:5], off nt
	v_or_b32_e32 v2, 48, v32
	v_or_b32_e32 v4, 56, v32
	v_mad_i64_i32 v[2:3], s[2:3], v2, s31, v[0:1]
	v_mad_i64_i32 v[0:1], s[2:3], v4, s31, v[0:1]
	global_load_dwordx4 v[4:7], v[2:3], off nt
	s_nop 0
	global_load_dwordx4 v[0:3], v[0:1], off nt
	v_cndmask_b32_e64 v33, 0, 1, s[6:7]
	v_cmp_ne_u32_e64 s[2:3], 1, v33
	s_andn2_b64 vcc, exec, s[6:7]
	s_cbranch_vccnz .LBB0_1619
	v_ashrrev_i32_e32 v33, 31, v32
	v_lshl_add_u64 v[32:33], v[32:33], 2, s[4:5]
	v_mov_b64_e32 v[196:197], v[32:33]
	global_load_dword v176, v[196:197], off offset:1024
	global_load_dword v178, v[196:197], off offset:1056
	global_load_dword v180, v[196:197], off offset:1088
	global_load_dword v182, v[196:197], off offset:1120
	global_load_dword v184, v[196:197], off offset:1152
	global_load_dword v186, v[196:197], off offset:1184
	global_load_dword v192, v[196:197], off offset:1216
	global_load_dword v194, v[196:197], off offset:1248
	s_waitcnt vmcnt(0) lgkmcnt(0)
	v_add_u32_e32 v66, v53, v46
	v_pk_mul_f32 v[34:35], v[26:27], v[176:177] op_sel_hi:[1,0]
	v_pk_mul_f32 v[32:33], v[24:25], v[176:177] op_sel_hi:[1,0]
	ds_write2_b32 v66, v32, v33 offset1:1
	ds_write2_b32 v66, v34, v35 offset0:2 offset1:3
	v_or_b32_e32 v32, s12, v47
	v_ashrrev_i32_e32 v33, 31, v32
	v_lshl_add_u64 v[32:33], v[32:33], 2, s[4:5]
	v_pk_mul_f32 v[34:35], v[30:31], v[178:179] op_sel_hi:[1,0]
	v_pk_mul_f32 v[32:33], v[28:29], v[178:179] op_sel_hi:[1,0]
	s_cbranch_execnz .LBB0_1611

.LBB0_1611:
	s_waitcnt vmcnt(0) lgkmcnt(0)
	v_add_u32_e32 v24, v53, v48
	s_and_b64 vcc, exec, s[2:3]
	ds_write2_b32 v24, v32, v33 offset1:1
	ds_write2_b32 v24, v34, v35 offset0:2 offset1:3
	s_cbranch_vccnz .LBB0_1620
	v_or_b32_e32 v24, s12, v49
	v_ashrrev_i32_e32 v25, 31, v24
	v_lshl_add_u64 v[24:25], v[24:25], 2, s[4:5]
	v_add_u32_e32 v28, v53, v50
	v_pk_mul_f32 v[26:27], v[18:19], v[180:181] op_sel_hi:[1,0]
	v_pk_mul_f32 v[24:25], v[16:17], v[180:181] op_sel_hi:[1,0]
	ds_write2_b32 v28, v24, v25 offset1:1
	ds_write2_b32 v28, v26, v27 offset0:2 offset1:3
	v_or_b32_e32 v24, s12, v51
	v_ashrrev_i32_e32 v25, 31, v24
	v_lshl_add_u64 v[24:25], v[24:25], 2, s[4:5]
	v_pk_mul_f32 v[26:27], v[22:23], v[182:183] op_sel_hi:[1,0]
	v_pk_mul_f32 v[24:25], v[20:21], v[182:183] op_sel_hi:[1,0]
	s_cbranch_execnz .LBB0_1614

.LBB0_1614:
	v_add_u32_e32 v16, v53, v52
	s_and_b64 vcc, exec, s[2:3]
	ds_write2_b32 v16, v24, v25 offset1:1
	ds_write2_b32 v16, v26, v27 offset0:2 offset1:3
	s_cbranch_vccnz .LBB0_1621
	s_ashr_i32 s13, s12, 31
	v_lshl_add_u64 v[16:17], s[12:13], 0, v[40:41]
	v_lshl_add_u64 v[16:17], v[16:17], 2, s[4:5]
	v_pk_mul_f32 v[20:21], v[10:11], v[184:185] op_sel_hi:[1,0]
	v_pk_mul_f32 v[18:19], v[8:9], v[184:185] op_sel_hi:[1,0]
	ds_write2_b32 v64, v18, v19 offset1:1
	ds_write2_b32 v64, v20, v21 offset0:2 offset1:3
	v_pk_mul_f32 v[18:19], v[14:15], v[186:187] op_sel_hi:[1,0]
	v_pk_mul_f32 v[16:17], v[12:13], v[186:187] op_sel_hi:[1,0]
	s_cbranch_execnz .LBB0_1617

.LBB0_1617:
	s_and_b64 vcc, exec, s[2:3]
	ds_write2_b32 v62, v16, v17 offset1:1
	ds_write2_b32 v62, v18, v19 offset0:2 offset1:3
	s_cbranch_vccnz .LBB0_1622
	s_ashr_i32 s13, s12, 31
	v_lshl_add_u64 v[8:9], s[12:13], 0, v[40:41]
	v_lshl_add_u64 v[8:9], v[8:9], 2, s[4:5]
	v_pk_mul_f32 v[12:13], v[6:7], v[192:193] op_sel_hi:[1,0]
	v_pk_mul_f32 v[10:11], v[4:5], v[192:193] op_sel_hi:[1,0]
	ds_write2_b32 v65, v10, v11 offset1:1
	ds_write2_b32 v65, v12, v13 offset0:2 offset1:3
	v_pk_mul_f32 v[10:11], v[2:3], v[194:195] op_sel_hi:[1,0]
	v_pk_mul_f32 v[8:9], v[0:1], v[194:195] op_sel_hi:[1,0]
	s_cbranch_execnz .LBB0_1607
	s_branch .LBB0_1623

.LBB0_1627:
	s_ashr_i32 s2, s26, 31
	s_lshr_b32 s2, s2, 28
	s_add_i32 s2, s26, s2
	s_ashr_i32 s2, s2, 4
	s_lshl_b32 s12, s2, 6
	s_lshl_b32 s19, s2, 9
	v_or_b32_e32 v32, s12, v40
	s_sub_i32 s2, s17, s19
	v_or_b32_e32 v4, 8, v32
	s_ashr_i32 s3, s2, 31
	v_ashrrev_i32_e32 v33, 31, v32
	v_ashrrev_i32_e32 v5, 31, v4
	v_lshl_add_u64 v[0:1], s[2:3], 2, v[38:39]
	v_lshlrev_b64 v[2:3], 11, v[32:33]
	v_lshlrev_b64 v[4:5], 11, v[4:5]
	v_lshl_add_u64 v[2:3], v[0:1], 0, v[2:3]
	v_lshl_add_u64 v[4:5], v[0:1], 0, v[4:5]
	global_load_dwordx4 v[24:27], v[2:3], off nt
	global_load_dwordx4 v[28:31], v[4:5], off nt
	v_or_b32_e32 v2, 16, v32
	v_or_b32_e32 v4, 24, v32
	v_ashrrev_i32_e32 v3, 31, v2
	v_ashrrev_i32_e32 v5, 31, v4
	v_lshlrev_b64 v[2:3], 11, v[2:3]
	v_lshlrev_b64 v[4:5], 11, v[4:5]
	v_lshl_add_u64 v[2:3], v[0:1], 0, v[2:3]
	v_lshl_add_u64 v[4:5], v[0:1], 0, v[4:5]
	global_load_dwordx4 v[16:19], v[2:3], off nt
	global_load_dwordx4 v[20:23], v[4:5], off nt
	v_or_b32_e32 v2, 32, v32
	v_or_b32_e32 v4, 40, v32
	v_ashrrev_i32_e32 v3, 31, v2
	v_ashrrev_i32_e32 v5, 31, v4
	v_lshlrev_b64 v[2:3], 11, v[2:3]
	v_lshlrev_b64 v[4:5], 11, v[4:5]
	v_lshl_add_u64 v[2:3], v[0:1], 0, v[2:3]
	v_lshl_add_u64 v[4:5], v[0:1], 0, v[4:5]
	global_load_dwordx4 v[8:11], v[2:3], off nt
	global_load_dwordx4 v[12:15], v[4:5], off nt
	v_or_b32_e32 v2, 48, v32
	v_or_b32_e32 v4, 56, v32
	v_ashrrev_i32_e32 v3, 31, v2
	v_ashrrev_i32_e32 v5, 31, v4
	v_lshlrev_b64 v[2:3], 11, v[2:3]
	v_lshlrev_b64 v[4:5], 11, v[4:5]
	v_lshl_add_u64 v[2:3], v[0:1], 0, v[2:3]
	v_lshl_add_u64 v[0:1], v[0:1], 0, v[4:5]
	global_load_dwordx4 v[4:7], v[2:3], off nt
	s_nop 0
	global_load_dwordx4 v[0:3], v[0:1], off nt
	v_cndmask_b32_e64 v34, 0, 1, s[10:11]
	v_cmp_ne_u32_e64 s[2:3], 1, v34
	s_andn2_b64 vcc, exec, s[10:11]
	v_add_u32_e32 v58, v53, v46
	s_cbranch_vccnz .LBB0_1638
	v_lshl_add_u64 v[32:33], v[32:33], 2, s[6:7]
	v_mov_b64_e32 v[196:197], v[32:33]
	global_load_dword v176, v[196:197], off offset:512
	global_load_dword v178, v[196:197], off offset:544
	global_load_dword v180, v[196:197], off offset:576
	global_load_dword v182, v[196:197], off offset:608
	global_load_dword v184, v[196:197], off offset:640
	global_load_dword v186, v[196:197], off offset:672
	global_load_dword v192, v[196:197], off offset:704
	global_load_dword v194, v[196:197], off offset:736
	s_waitcnt vmcnt(0) lgkmcnt(0)
	v_pk_mul_f32 v[34:35], v[26:27], v[176:177] op_sel_hi:[1,0]
	v_pk_mul_f32 v[32:33], v[24:25], v[176:177] op_sel_hi:[1,0]
	ds_write2_b32 v58, v32, v33 offset1:1
	ds_write2_b32 v58, v34, v35 offset0:2 offset1:3
	v_or_b32_e32 v32, s12, v47
	v_ashrrev_i32_e32 v33, 31, v32
	v_lshl_add_u64 v[32:33], v[32:33], 2, s[6:7]
	v_pk_mul_f32 v[34:35], v[30:31], v[178:179] op_sel_hi:[1,0]
	v_pk_mul_f32 v[32:33], v[28:29], v[178:179] op_sel_hi:[1,0]
	s_cbranch_execnz .LBB0_1630

.LBB0_1630:
	s_waitcnt vmcnt(0) lgkmcnt(0)
	v_add_u32_e32 v24, v53, v48
	s_and_b64 vcc, exec, s[2:3]
	v_add_u32_e32 v28, v53, v50
	ds_write2_b32 v24, v32, v33 offset1:1
	ds_write2_b32 v24, v34, v35 offset0:2 offset1:3
	s_cbranch_vccnz .LBB0_1639
	v_or_b32_e32 v24, s12, v49
	v_ashrrev_i32_e32 v25, 31, v24
	v_lshl_add_u64 v[24:25], v[24:25], 2, s[6:7]
	v_pk_mul_f32 v[26:27], v[18:19], v[180:181] op_sel_hi:[1,0]
	v_pk_mul_f32 v[24:25], v[16:17], v[180:181] op_sel_hi:[1,0]
	ds_write2_b32 v28, v24, v25 offset1:1
	ds_write2_b32 v28, v26, v27 offset0:2 offset1:3
	v_or_b32_e32 v24, s12, v51
	v_ashrrev_i32_e32 v25, 31, v24
	v_lshl_add_u64 v[24:25], v[24:25], 2, s[6:7]
	v_pk_mul_f32 v[26:27], v[22:23], v[182:183] op_sel_hi:[1,0]
	v_pk_mul_f32 v[24:25], v[20:21], v[182:183] op_sel_hi:[1,0]
	s_cbranch_execnz .LBB0_1633

.LBB0_1633:
	v_add_u32_e32 v16, v53, v52
	s_and_b64 vcc, exec, s[2:3]
	ds_write2_b32 v16, v24, v25 offset1:1
	ds_write2_b32 v16, v26, v27 offset0:2 offset1:3
	s_cbranch_vccnz .LBB0_1640
	s_ashr_i32 s13, s12, 31
	v_lshl_add_u64 v[16:17], s[12:13], 0, v[40:41]
	v_lshl_add_u64 v[16:17], v[16:17], 2, s[6:7]
	v_pk_mul_f32 v[20:21], v[10:11], v[184:185] op_sel_hi:[1,0]
	v_pk_mul_f32 v[18:19], v[8:9], v[184:185] op_sel_hi:[1,0]
	ds_write2_b32 v44, v18, v19 offset1:1
	ds_write2_b32 v44, v20, v21 offset0:2 offset1:3
	v_pk_mul_f32 v[18:19], v[14:15], v[186:187] op_sel_hi:[1,0]
	v_pk_mul_f32 v[16:17], v[12:13], v[186:187] op_sel_hi:[1,0]
	s_cbranch_execnz .LBB0_1636

.LBB0_1636:
	s_and_b64 vcc, exec, s[2:3]
	ds_write2_b32 v42, v16, v17 offset1:1
	ds_write2_b32 v42, v18, v19 offset0:2 offset1:3
	s_cbranch_vccnz .LBB0_1641
	s_ashr_i32 s13, s12, 31
	v_lshl_add_u64 v[8:9], s[12:13], 0, v[40:41]
	v_lshl_add_u64 v[8:9], v[8:9], 2, s[6:7]
	v_pk_mul_f32 v[12:13], v[6:7], v[192:193] op_sel_hi:[1,0]
	v_pk_mul_f32 v[10:11], v[4:5], v[192:193] op_sel_hi:[1,0]
	ds_write2_b32 v45, v10, v11 offset1:1
	ds_write2_b32 v45, v12, v13 offset0:2 offset1:3
	v_pk_mul_f32 v[10:11], v[2:3], v[194:195] op_sel_hi:[1,0]
	v_pk_mul_f32 v[8:9], v[0:1], v[194:195] op_sel_hi:[1,0]
	s_cbranch_execnz .LBB0_1626
	s_branch .LBB0_1642
